# hand-scheduled swiglu (MODE 0) GEMM epilogue: 8 interleaved silu chains per row, no hazard nops, incremental row addresses
# speedup vs baseline: 1.0119x; 1.0036x over previous
; #define AT_LOADK(kt) do { kA = *(const u32x4*)(kp0 + (size_t)(kt) * ks0); if (tid < 256) kB = *(const u32x4*)(kp1 + (size_t)(kt) * ks1); } while (0)
; #define AT_LOADV(kt) do { vR = *(const u32x4*)(vp0 + (kt) * 64); } while (0)
; #define AT_STOREK(bi) do { bf16_t* Kw_ = (bf16_t*)(lds + (bi) * AT_KB); *(u32x4*)(Kw_ + key0 * AK + part0 * 8) = kA; if (tid < 256) *(u32x4*)(Kw_ + key1 * AK + part1 * 8) = kB; } while (0)
; #define AT_STOREV(bi) do { bf16_t* Vw_ = (bf16_t*)(lds + 2 * AT_KB + (bi) * AT_VB); *(u32x4*)(Vw_ + ve * AV + vpart * 8) = vR; } while (0)
; #define AT_QK(P0, P1, bi, CI) do { const bf16_t* Kt_ = (const bf16_t*)(lds + (bi) * AT_KB); P0 = CI; P1 = CI; \
;         _Pragma("unroll") for (int s = 0; s < 6; ++s) { const bf16x8 a0_ = *(const bf16x8*)(Kt_ + r32 * AK + 16 * s + 8 * hi), a1_ = *(const bf16x8*)(Kt_ + (32 + r32) * AK + 16 * s + 8 * hi); \
;             P0 = MFMA32(a0_, qr[s], P0); P1 = MFMA32(a1_, qr[s], P1); } } while (0)
; __device__ __forceinline__ void attn_unit(const Params& P, unsigned char* lds, int b, int h, int qb, int tid) {
;     ...
;     float mref, l_part = 0.f;
;     f32x16 o0, o1, negm, sa0, sa1, sb0, sb1;
; #pragma unroll
;     for (int i = 0; i < 16; ++i) { o0[i] = 0.f; o1[i] = 0.f; negm[i] = 0.f; }
;     AT_LOADK(0); AT_LOADV(0); AT_STOREK(0); AT_STOREV(0); AT_LOADK(1);
;     __syncthreads();
;     AT_QK(sa0, sa1, 0, negm);
;     { float mx = fmaxf(sa0[0], sa1[0]);
; #pragma unroll
;       for (int i = 1; i < 16; ++i) mx = fmaxf(mx, fmaxf(sa0[i], sa1[i]));
;       { auto rr_ = __builtin_amdgcn_permlane32_swap(__float_as_uint(mx), __float_as_uint(mx), false, false); mx = fmaxf(__uint_as_float(rr_[0]), __uint_as_float(rr_[1])); }
;       mref = mx;
; #pragma unroll
;       for (int i = 0; i < 16; ++i) { sa0[i] -= mx; sa1[i] -= mx; negm[i] = -mx; } }
;     AT_STOREK(1); AT_LOADK(2); AT_LOADV(1);
;     __syncthreads();
.LBB0_168:
	s_or_b64 exec, exec, s[10:11]
	s_mov_b64 s[10:11], 0xac00000
	v_lshl_add_u64 v[46:47], v[36:37], 0, s[10:11]
	global_load_dwordx4 v[144:147], v[46:47], off offset:128
	v_max_f32_e32 v32, v44, v44
	v_max_f32_e32 v33, v42, v42
	v_max_f32_e32 v225, v33, v32
	v_sub_f32_e32 v182, v0, v225
	v_and_b32_e32 v0, 0x3fffffc0, v49
	v_lshl_add_u32 v226, v0, 2, 0
	v_lshlrev_b32_e32 v0, 6, v222
	v_sub_u32_e32 v0, v56, v0
	v_lshl_add_u32 v229, v64, 1, v0
	v_and_b32_e32 v0, 7, v49
	v_sub_f32_e32 v183, v1, v225
	v_lshlrev_b32_e32 v0, 4, v0
	v_mov_b32_e32 v1, v153
	v_sub_f32_e32 v184, v2, v225
	v_sub_f32_e32 v185, v3, v225
	v_lshl_add_u64 v[0:1], v[52:53], 0, v[0:1]
	v_add_u32_e32 v2, v51, v54
	v_mov_b32_e32 v3, v153
	v_lshl_add_u64 v[0:1], v[2:3], 1, v[0:1]
	v_sub_f32_e32 v196, v14, v225
	v_sub_f32_e32 v197, v15, v225
	v_lshl_add_u64 v[0:1], s[12:13], 0, v[0:1]
	s_mov_b64 s[10:11], 0xac00180
	v_mov_b32_e32 v14, v153
	v_mov_b32_e32 v15, v153
	v_xor_b32_e32 v48, 0x80000000, v225
	v_sub_f32_e32 v32, v16, v225
	v_sub_f32_e32 v33, v17, v225
	v_sub_f32_e32 v34, v18, v225
	v_sub_f32_e32 v35, v19, v225
	v_sub_f32_e32 v36, v20, v225
	v_sub_f32_e32 v37, v21, v225
	v_sub_f32_e32 v38, v22, v225
	v_sub_f32_e32 v39, v23, v225
	v_sub_f32_e32 v40, v24, v225
	v_sub_f32_e32 v41, v25, v225
	v_sub_f32_e32 v42, v26, v225
	v_sub_f32_e32 v43, v27, v225
	v_sub_f32_e32 v44, v28, v225
	v_sub_f32_e32 v45, v29, v225
	v_sub_f32_e32 v46, v30, v225
	v_sub_f32_e32 v47, v31, v225
	v_sub_f32_e32 v186, v4, v225
	v_sub_f32_e32 v187, v5, v225
	v_sub_f32_e32 v188, v6, v225
	v_sub_f32_e32 v189, v7, v225
	v_sub_f32_e32 v190, v8, v225
	v_sub_f32_e32 v191, v9, v225
	v_sub_f32_e32 v192, v10, v225
	v_sub_f32_e32 v193, v11, v225
	v_sub_f32_e32 v194, v12, v225
	v_sub_f32_e32 v195, v13, v225
	v_lshl_add_u64 v[176:177], v[0:1], 0, s[10:11]
	v_mov_b32_e32 v0, v153
	v_mov_b32_e32 v1, v153
	v_mov_b32_e32 v2, v153
	v_mov_b32_e32 v4, v153
	v_mov_b32_e32 v5, v153
	v_mov_b32_e32 v6, v153
	v_mov_b32_e32 v7, v153
	v_mov_b32_e32 v8, v153
	v_mov_b32_e32 v9, v153
	v_mov_b32_e32 v10, v153
	v_mov_b32_e32 v11, v153
	v_mov_b32_e32 v12, v153
	v_mov_b32_e32 v13, v153
	v_mov_b64_e32 v[30:31], v[14:15]
	v_add_u32_e32 v228, 0, v55
	v_cndmask_b32_e64 v174, 11, 16, s[8:9]
	v_cmp_eq_u32_e64 s[8:9], 0, v223
	v_lshl_add_u32 v227, v222, 2, v226
	v_lshlrev_b32_e32 v178, 3, v50
	v_mov_b32_e32 v179, v153
	v_mul_hi_u32_u24_e32 v181, 6, v50
	v_mul_u32_u24_e32 v180, 6, v50
	v_mov_b32_e32 v230, 0
	s_mov_b64 s[92:93], 4
	v_mov_b64_e32 v[28:29], v[12:13]
	v_mov_b64_e32 v[26:27], v[10:11]
	v_mov_b64_e32 v[24:25], v[8:9]
	v_mov_b64_e32 v[22:23], v[6:7]
	v_mov_b64_e32 v[20:21], v[4:5]
	v_mov_b64_e32 v[18:19], v[2:3]
	v_mov_b64_e32 v[16:17], v[0:1]
	v_mov_b32_e32 v49, v48
	v_mov_b32_e32 v50, v48
	v_mov_b32_e32 v51, v48
	v_mov_b32_e32 v52, v48
	v_mov_b32_e32 v53, v48
	v_mov_b32_e32 v54, v48
	v_mov_b32_e32 v55, v48
	v_mov_b32_e32 v56, v48
	v_mov_b32_e32 v57, v48
	v_mov_b32_e32 v58, v48
	v_mov_b32_e32 v59, v48
	v_mov_b32_e32 v60, v48
	v_mov_b32_e32 v61, v48
	v_mov_b32_e32 v62, v48
	v_mov_b32_e32 v63, v48
	s_mov_b64 s[10:11], 3
	v_lshlrev_b64 v[204:205], v174, s[10:11]
	v_lshl_add_u64 v[204:205], v[204:205], 1, v[166:167]
	global_load_dwordx4 v[204:207], v[204:205], off
	v_lshl_add_u64 v[198:199], v[170:171], 0, v[180:181]
	global_load_dwordx4 v[198:201], v[198:199], off
	global_load_dwordx4 v[208:211], v[176:177], off offset:-128
	v_readfirstlane_b32 s10, v217
	s_cmpk_lt_u32 s10, 0x100
	s_cbranch_scc1 .Latt_noprio
	s_setprio 1

.LBB0_170:
	s_add_i32 s18, s92, -4
	s_cmp_lt_u32 s18, 62
	s_cselect_b64 s[12:13], -1, 0
	s_cmp_gt_u32 s18, 61
	s_cbranch_scc1 .LBB0_174
	s_waitcnt vmcnt(3)
	ds_write_b128 v163, v[140:143]
	s_and_saveexec_b64 s[10:11], s[6:7]
	v_add_u32_e32 v64, v228, v168
	ds_write_b128 v64, v[112:115]
	s_or_b64 exec, exec, s[10:11]
.LBB0_174:
	s_cmp_lt_u32 s18, 61
	s_cselect_b64 s[28:29], -1, 0
	s_cmp_gt_u32 s18, 60
	s_waitcnt vmcnt(3)
	ds_write_b128 v165, v[144:147] offset:35840
	s_mov_b64 s[10:11], s[92:93]
	v_lshlrev_b64 v[64:65], v174, s[10:11]
	v_lshl_add_u64 v[64:65], v[64:65], 1, v[166:167]
	global_load_dwordx4 v[140:143], v[64:65], off
	v_lshl_add_u64 v[64:65], v[170:171], 0, v[178:179]
	global_load_dwordx4 v[112:115], v[64:65], off
.LBB0_177:
.LBB0_178:
	v_cndmask_b32_e64 v64, 0, 1, s[12:13]
	v_cmp_ne_u32_e64 s[10:11], 1, v64
	s_andn2_b64 vcc, exec, s[12:13]
	global_load_dwordx4 v[144:147], v[176:177], off

.LBB0_190:
	s_waitcnt vmcnt(3)
	ds_write_b128 v163, v[204:207] offset:13312
	s_and_saveexec_b64 s[28:29], s[6:7]
	v_add_u32_e32 v148, v228, v168
	ds_write_b128 v148, v[198:201] offset:13312
	s_or_b64 exec, exec, s[28:29]
	s_and_b64 vcc, exec, s[10:11]
	s_cbranch_vccnz .LBB0_184
.LBB0_193:
	s_waitcnt vmcnt(3)
	ds_write_b128 v165, v[208:211] offset:26624
	s_cmp_gt_u32 s18, 59
.LBB0_194:
	s_waitcnt vmcnt(3)
	s_add_u32 s28, s92, 1
	s_addc_u32 s29, s93, 0
	v_lshlrev_b64 v[204:205], v174, s[28:29]
	v_lshl_add_u64 v[204:205], v[204:205], 1, v[166:167]
	global_load_dwordx4 v[204:207], v[204:205], off
	v_lshl_add_u64 v[198:199], v[170:171], 0, v[180:181]
	v_lshl_add_u64 v[198:199], v[198:199], 0, v[172:173]
	global_load_dwordx4 v[198:201], v[198:199], off
.LBB0_196:
	s_and_b64 vcc, exec, s[12:13]
	s_branch .LBB0_186

; __device__ __forceinline__ unsigned pk_bf16_rne(float lo, float hi) { f32x2 v = {lo, hi}; bf16x2e b = __builtin_convertvector(v, bf16x2e); return __builtin_bit_cast(unsigned, b); }
; __device__ __forceinline__ float silu_f(float x) { return x * __builtin_amdgcn_rcpf(1.0f + __expf(-x)); }
;     __device__ __forceinline__ void operator()(const f32x4 (&acc)[2][2][4][2], const Unit& u, int wr, int wc, int fr, int fq) const {
; #pragma unroll
;         for (int ai = 0; ai < 2; ++ai)
; #pragma unroll
;             for (int m = 0; m < 4; ++m) {
;                 const int r = u.pm * BM + ai * HALF + wr * 64 + m * 16 + fr;
; #pragma unroll
;                 for (int bj = 0; bj < 2; ++bj) {
;                     const int cb = u.pn * BM + bj * HALF + wc * 32;
;                     const f32x4 v0 = acc[ai][bj][m][0], v1 = acc[ai][bj][m][1];
;                     if (MODE == 0) {
;                         u32x2e w; w.x = pk_bf16_rne(silu_f(v0[0]) * v1[0], silu_f(v0[1]) * v1[1]); w.y = pk_bf16_rne(silu_f(v0[2]) * v1[2], silu_f(v0[3]) * v1[3]);
;                         *(u32x2e*)(Hh + (size_t)r * ldo + (cb >> 1) + 4 * fq) = w;
.LBB0_449:
	s_lshl_b32 s25, s24, 8
	s_add_i32 s25, s25, s45
	s_ashr_i32 s4, s25, 12
	v_or_b32_e32 v138, s25, v146
	s_mul_i32 s88, s4, 0x2400
	s_lshl_b32 s4, s41, 8
	v_ashrrev_i32_e32 v139, 31, v138
	s_ashr_i32 s89, s88, 31
	s_or_b32 s86, s4, s37
	v_lshlrev_b64 v[144:145], 10, v[138:139]
	v_lshlrev_b64 v[142:143], 11, v[138:139]
	v_lshlrev_b64 v[140:141], 12, v[138:139]
	s_cmp_eq_u32 s66, 0
	s_cbranch_scc0 .Lepi0_skip
	v_mul_lo_u32 v160, v138, s67
	v_mov_b32_e32 v161, 0
	v_lshl_add_u32 v162, v132, 1, s86
	v_mov_b32_e32 v163, 0
	v_lshl_add_u64 v[160:161], v[160:161], 1, s[74:75]
	s_mov_b32 s4, 0x16000
	s_mov_b32 s5, 0
	s_mov_b32 s28, 0x6e000
	s_mov_b32 s29, 0
	v_lshl_add_u64 v[160:161], v[160:161], 0, v[162:163]
	v_mul_f32_e32 v164, 0xbfb8aa3b, v124
	v_mul_f32_e32 v165, 0xbfb8aa3b, v125
	v_mul_f32_e32 v166, 0xbfb8aa3b, v126
	v_mul_f32_e32 v167, 0xbfb8aa3b, v127
	v_mul_f32_e32 v168, 0xbfb8aa3b, v116
	v_mul_f32_e32 v169, 0xbfb8aa3b, v117
	v_mul_f32_e32 v170, 0xbfb8aa3b, v118
	v_mul_f32_e32 v171, 0xbfb8aa3b, v119
	v_exp_f32_e32 v164, v164
	v_exp_f32_e32 v165, v165
	v_exp_f32_e32 v166, v166
	v_exp_f32_e32 v167, v167
	v_exp_f32_e32 v168, v168
	v_exp_f32_e32 v169, v169
	v_exp_f32_e32 v170, v170
	v_exp_f32_e32 v171, v171
	v_add_f32_e32 v164, 1.0, v164
	v_add_f32_e32 v165, 1.0, v165
	v_add_f32_e32 v166, 1.0, v166
	v_add_f32_e32 v167, 1.0, v167
	v_add_f32_e32 v168, 1.0, v168
	v_add_f32_e32 v169, 1.0, v169
	v_add_f32_e32 v170, 1.0, v170
	v_add_f32_e32 v171, 1.0, v171
	v_rcp_f32_e32 v164, v164
	v_rcp_f32_e32 v165, v165
	v_rcp_f32_e32 v166, v166
	v_rcp_f32_e32 v167, v167
	v_rcp_f32_e32 v168, v168
	v_rcp_f32_e32 v169, v169
	v_rcp_f32_e32 v170, v170
	v_rcp_f32_e32 v171, v171
	v_pk_mul_f32 v[124:125], v[124:125], v[164:165]
	v_pk_mul_f32 v[126:127], v[126:127], v[166:167]
	v_pk_mul_f32 v[116:117], v[116:117], v[168:169]
	v_pk_mul_f32 v[118:119], v[118:119], v[170:171]
	v_pk_mul_f32 v[124:125], v[120:121], v[124:125]
	v_pk_mul_f32 v[126:127], v[122:123], v[126:127]
	v_pk_mul_f32 v[116:117], v[112:113], v[116:117]
	v_pk_mul_f32 v[118:119], v[114:115], v[118:119]
	v_cvt_pk_bf16_f32 v176, v124, v125
	v_cvt_pk_bf16_f32 v177, v126, v127
	v_cvt_pk_bf16_f32 v178, v116, v117
	v_cvt_pk_bf16_f32 v179, v118, v119
	global_store_dwordx2 v[160:161], v[176:177], off
	global_store_dwordx2 v[160:161], v[178:179], off offset:128
	s_nop 1
	v_lshl_add_u64 v[160:161], v[160:161], 0, s[4:5]
	v_mul_f32_e32 v164, 0xbfb8aa3b, v108
	v_mul_f32_e32 v165, 0xbfb8aa3b, v109
	v_mul_f32_e32 v166, 0xbfb8aa3b, v110
	v_mul_f32_e32 v167, 0xbfb8aa3b, v111
	v_mul_f32_e32 v168, 0xbfb8aa3b, v100
	v_mul_f32_e32 v169, 0xbfb8aa3b, v101
	v_mul_f32_e32 v170, 0xbfb8aa3b, v102
	v_mul_f32_e32 v171, 0xbfb8aa3b, v103
	v_exp_f32_e32 v164, v164
	v_exp_f32_e32 v165, v165
	v_exp_f32_e32 v166, v166
	v_exp_f32_e32 v167, v167
	v_exp_f32_e32 v168, v168
	v_exp_f32_e32 v169, v169
	v_exp_f32_e32 v170, v170
	v_exp_f32_e32 v171, v171
	v_add_f32_e32 v164, 1.0, v164
	v_add_f32_e32 v165, 1.0, v165
	v_add_f32_e32 v166, 1.0, v166
	v_add_f32_e32 v167, 1.0, v167
	v_add_f32_e32 v168, 1.0, v168
	v_add_f32_e32 v169, 1.0, v169
	v_add_f32_e32 v170, 1.0, v170
	v_add_f32_e32 v171, 1.0, v171
	v_rcp_f32_e32 v164, v164
	v_rcp_f32_e32 v165, v165
	v_rcp_f32_e32 v166, v166
	v_rcp_f32_e32 v167, v167
	v_rcp_f32_e32 v168, v168
	v_rcp_f32_e32 v169, v169
	v_rcp_f32_e32 v170, v170
	v_rcp_f32_e32 v171, v171
	v_pk_mul_f32 v[108:109], v[108:109], v[164:165]
	v_pk_mul_f32 v[110:111], v[110:111], v[166:167]
	v_pk_mul_f32 v[100:101], v[100:101], v[168:169]
	v_pk_mul_f32 v[102:103], v[102:103], v[170:171]
	v_pk_mul_f32 v[108:109], v[104:105], v[108:109]
	v_pk_mul_f32 v[110:111], v[106:107], v[110:111]
	v_pk_mul_f32 v[100:101], v[96:97], v[100:101]
	v_pk_mul_f32 v[102:103], v[98:99], v[102:103]
	v_cvt_pk_bf16_f32 v180, v108, v109
	v_cvt_pk_bf16_f32 v181, v110, v111
	v_cvt_pk_bf16_f32 v182, v100, v101
	v_cvt_pk_bf16_f32 v183, v102, v103
	global_store_dwordx2 v[160:161], v[180:181], off
	global_store_dwordx2 v[160:161], v[182:183], off offset:128
	s_nop 1
	v_lshl_add_u64 v[160:161], v[160:161], 0, s[4:5]
	v_mul_f32_e32 v164, 0xbfb8aa3b, v92
	v_mul_f32_e32 v165, 0xbfb8aa3b, v93
	v_mul_f32_e32 v166, 0xbfb8aa3b, v94
	v_mul_f32_e32 v167, 0xbfb8aa3b, v95
	v_mul_f32_e32 v168, 0xbfb8aa3b, v84
	v_mul_f32_e32 v169, 0xbfb8aa3b, v85
	v_mul_f32_e32 v170, 0xbfb8aa3b, v86
	v_mul_f32_e32 v171, 0xbfb8aa3b, v87
	v_exp_f32_e32 v164, v164
	v_exp_f32_e32 v165, v165
	v_exp_f32_e32 v166, v166
	v_exp_f32_e32 v167, v167
	v_exp_f32_e32 v168, v168
	v_exp_f32_e32 v169, v169
	v_exp_f32_e32 v170, v170
	v_exp_f32_e32 v171, v171
	v_add_f32_e32 v164, 1.0, v164
	v_add_f32_e32 v165, 1.0, v165
	v_add_f32_e32 v166, 1.0, v166
	v_add_f32_e32 v167, 1.0, v167
	v_add_f32_e32 v168, 1.0, v168
	v_add_f32_e32 v169, 1.0, v169
	v_add_f32_e32 v170, 1.0, v170
	v_add_f32_e32 v171, 1.0, v171
	v_rcp_f32_e32 v164, v164
	v_rcp_f32_e32 v165, v165
	v_rcp_f32_e32 v166, v166
	v_rcp_f32_e32 v167, v167
	v_rcp_f32_e32 v168, v168
	v_rcp_f32_e32 v169, v169
	v_rcp_f32_e32 v170, v170
	v_rcp_f32_e32 v171, v171
	v_pk_mul_f32 v[92:93], v[92:93], v[164:165]
	v_pk_mul_f32 v[94:95], v[94:95], v[166:167]
	v_pk_mul_f32 v[84:85], v[84:85], v[168:169]
	v_pk_mul_f32 v[86:87], v[86:87], v[170:171]
	v_pk_mul_f32 v[92:93], v[88:89], v[92:93]
	v_pk_mul_f32 v[94:95], v[90:91], v[94:95]
	v_pk_mul_f32 v[84:85], v[80:81], v[84:85]
	v_pk_mul_f32 v[86:87], v[82:83], v[86:87]
	v_cvt_pk_bf16_f32 v176, v92, v93
	v_cvt_pk_bf16_f32 v177, v94, v95
	v_cvt_pk_bf16_f32 v178, v84, v85
	v_cvt_pk_bf16_f32 v179, v86, v87
	global_store_dwordx2 v[160:161], v[176:177], off
	global_store_dwordx2 v[160:161], v[178:179], off offset:128
	s_nop 1
; __device__ __forceinline__ unsigned pk_bf16_rne(float lo, float hi) { f32x2 v = {lo, hi}; bf16x2e b = __builtin_convertvector(v, bf16x2e); return __builtin_bit_cast(unsigned, b); }
; __device__ __forceinline__ float silu_f(float x) { return x * __builtin_amdgcn_rcpf(1.0f + __expf(-x)); }
;     __device__ __forceinline__ void operator()(const f32x4 (&acc)[2][2][4][2], const Unit& u, int wr, int wc, int fr, int fq) const {
; #pragma unroll
;         for (int ai = 0; ai < 2; ++ai)
; #pragma unroll
;             for (int m = 0; m < 4; ++m) {
;                 const int r = u.pm * BM + ai * HALF + wr * 64 + m * 16 + fr;
; #pragma unroll
;                 for (int bj = 0; bj < 2; ++bj) {
;                     const int cb = u.pn * BM + bj * HALF + wc * 32;
;                     const f32x4 v0 = acc[ai][bj][m][0], v1 = acc[ai][bj][m][1];
;                     if (MODE == 0) {
;                         u32x2e w; w.x = pk_bf16_rne(silu_f(v0[0]) * v1[0], silu_f(v0[1]) * v1[1]); w.y = pk_bf16_rne(silu_f(v0[2]) * v1[2], silu_f(v0[3]) * v1[3]);
;                         *(u32x2e*)(Hh + (size_t)r * ldo + (cb >> 1) + 4 * fq) = w;
	v_lshl_add_u64 v[160:161], v[160:161], 0, s[4:5]
	v_mul_f32_e32 v164, 0xbfb8aa3b, v76
	v_mul_f32_e32 v165, 0xbfb8aa3b, v77
	v_mul_f32_e32 v166, 0xbfb8aa3b, v78
	v_mul_f32_e32 v167, 0xbfb8aa3b, v79
	v_mul_f32_e32 v168, 0xbfb8aa3b, v68
	v_mul_f32_e32 v169, 0xbfb8aa3b, v69
	v_mul_f32_e32 v170, 0xbfb8aa3b, v70
	v_mul_f32_e32 v171, 0xbfb8aa3b, v71
	v_exp_f32_e32 v164, v164
	v_exp_f32_e32 v165, v165
	v_exp_f32_e32 v166, v166
	v_exp_f32_e32 v167, v167
	v_exp_f32_e32 v168, v168
	v_exp_f32_e32 v169, v169
	v_exp_f32_e32 v170, v170
	v_exp_f32_e32 v171, v171
	v_add_f32_e32 v164, 1.0, v164
	v_add_f32_e32 v165, 1.0, v165
	v_add_f32_e32 v166, 1.0, v166
	v_add_f32_e32 v167, 1.0, v167
	v_add_f32_e32 v168, 1.0, v168
	v_add_f32_e32 v169, 1.0, v169
	v_add_f32_e32 v170, 1.0, v170
	v_add_f32_e32 v171, 1.0, v171
	v_rcp_f32_e32 v164, v164
	v_rcp_f32_e32 v165, v165
	v_rcp_f32_e32 v166, v166
	v_rcp_f32_e32 v167, v167
	v_rcp_f32_e32 v168, v168
	v_rcp_f32_e32 v169, v169
	v_rcp_f32_e32 v170, v170
	v_rcp_f32_e32 v171, v171
	v_pk_mul_f32 v[76:77], v[76:77], v[164:165]
	v_pk_mul_f32 v[78:79], v[78:79], v[166:167]
	v_pk_mul_f32 v[68:69], v[68:69], v[168:169]
	v_pk_mul_f32 v[70:71], v[70:71], v[170:171]
	v_pk_mul_f32 v[76:77], v[72:73], v[76:77]
	v_pk_mul_f32 v[78:79], v[74:75], v[78:79]
	v_pk_mul_f32 v[68:69], v[64:65], v[68:69]
	v_pk_mul_f32 v[70:71], v[66:67], v[70:71]
	v_cvt_pk_bf16_f32 v180, v76, v77
	v_cvt_pk_bf16_f32 v181, v78, v79
	v_cvt_pk_bf16_f32 v182, v68, v69
	v_cvt_pk_bf16_f32 v183, v70, v71
	global_store_dwordx2 v[160:161], v[180:181], off
	global_store_dwordx2 v[160:161], v[182:183], off offset:128
	s_nop 1
	v_lshl_add_u64 v[160:161], v[160:161], 0, s[28:29]
	v_mul_f32_e32 v164, 0xbfb8aa3b, v60
	v_mul_f32_e32 v165, 0xbfb8aa3b, v61
	v_mul_f32_e32 v166, 0xbfb8aa3b, v62
	v_mul_f32_e32 v167, 0xbfb8aa3b, v63
	v_mul_f32_e32 v168, 0xbfb8aa3b, v52
	v_mul_f32_e32 v169, 0xbfb8aa3b, v53
	v_mul_f32_e32 v170, 0xbfb8aa3b, v54
	v_mul_f32_e32 v171, 0xbfb8aa3b, v55
	v_exp_f32_e32 v164, v164
	v_exp_f32_e32 v165, v165
	v_exp_f32_e32 v166, v166
	v_exp_f32_e32 v167, v167
	v_exp_f32_e32 v168, v168
	v_exp_f32_e32 v169, v169
	v_exp_f32_e32 v170, v170
	v_exp_f32_e32 v171, v171
	v_add_f32_e32 v164, 1.0, v164
	v_add_f32_e32 v165, 1.0, v165
	v_add_f32_e32 v166, 1.0, v166
	v_add_f32_e32 v167, 1.0, v167
	v_add_f32_e32 v168, 1.0, v168
	v_add_f32_e32 v169, 1.0, v169
	v_add_f32_e32 v170, 1.0, v170
	v_add_f32_e32 v171, 1.0, v171
	v_rcp_f32_e32 v164, v164
	v_rcp_f32_e32 v165, v165
	v_rcp_f32_e32 v166, v166
	v_rcp_f32_e32 v167, v167
	v_rcp_f32_e32 v168, v168
	v_rcp_f32_e32 v169, v169
	v_rcp_f32_e32 v170, v170
	v_rcp_f32_e32 v171, v171
	v_pk_mul_f32 v[60:61], v[60:61], v[164:165]
	v_pk_mul_f32 v[62:63], v[62:63], v[166:167]
	v_pk_mul_f32 v[52:53], v[52:53], v[168:169]
	v_pk_mul_f32 v[54:55], v[54:55], v[170:171]
	v_pk_mul_f32 v[60:61], v[56:57], v[60:61]
	v_pk_mul_f32 v[62:63], v[58:59], v[62:63]
	v_pk_mul_f32 v[52:53], v[48:49], v[52:53]
	v_pk_mul_f32 v[54:55], v[50:51], v[54:55]
	v_cvt_pk_bf16_f32 v176, v60, v61
	v_cvt_pk_bf16_f32 v177, v62, v63
	v_cvt_pk_bf16_f32 v178, v52, v53
	v_cvt_pk_bf16_f32 v179, v54, v55
	global_store_dwordx2 v[160:161], v[176:177], off
	global_store_dwordx2 v[160:161], v[178:179], off offset:128
	s_nop 1
	v_lshl_add_u64 v[160:161], v[160:161], 0, s[4:5]
	v_mul_f32_e32 v164, 0xbfb8aa3b, v44
	v_mul_f32_e32 v165, 0xbfb8aa3b, v45
	v_mul_f32_e32 v166, 0xbfb8aa3b, v46
	v_mul_f32_e32 v167, 0xbfb8aa3b, v47
	v_mul_f32_e32 v168, 0xbfb8aa3b, v36
	v_mul_f32_e32 v169, 0xbfb8aa3b, v37
	v_mul_f32_e32 v170, 0xbfb8aa3b, v38
	v_mul_f32_e32 v171, 0xbfb8aa3b, v39
	v_exp_f32_e32 v164, v164
	v_exp_f32_e32 v165, v165
	v_exp_f32_e32 v166, v166
	v_exp_f32_e32 v167, v167
	v_exp_f32_e32 v168, v168
	v_exp_f32_e32 v169, v169
	v_exp_f32_e32 v170, v170
	v_exp_f32_e32 v171, v171
	v_add_f32_e32 v164, 1.0, v164
	v_add_f32_e32 v165, 1.0, v165
	v_add_f32_e32 v166, 1.0, v166
	v_add_f32_e32 v167, 1.0, v167
	v_add_f32_e32 v168, 1.0, v168
	v_add_f32_e32 v169, 1.0, v169
	v_add_f32_e32 v170, 1.0, v170
	v_add_f32_e32 v171, 1.0, v171
; __device__ __forceinline__ unsigned pk_bf16_rne(float lo, float hi) { f32x2 v = {lo, hi}; bf16x2e b = __builtin_convertvector(v, bf16x2e); return __builtin_bit_cast(unsigned, b); }
; __device__ __forceinline__ float silu_f(float x) { return x * __builtin_amdgcn_rcpf(1.0f + __expf(-x)); }
;     __device__ __forceinline__ void operator()(const f32x4 (&acc)[2][2][4][2], const Unit& u, int wr, int wc, int fr, int fq) const {
; #pragma unroll
;         for (int ai = 0; ai < 2; ++ai)
; #pragma unroll
;             for (int m = 0; m < 4; ++m) {
;                 const int r = u.pm * BM + ai * HALF + wr * 64 + m * 16 + fr;
; #pragma unroll
;                 for (int bj = 0; bj < 2; ++bj) {
;                     const int cb = u.pn * BM + bj * HALF + wc * 32;
;                     const f32x4 v0 = acc[ai][bj][m][0], v1 = acc[ai][bj][m][1];
;                     if (MODE == 0) {
;                         u32x2e w; w.x = pk_bf16_rne(silu_f(v0[0]) * v1[0], silu_f(v0[1]) * v1[1]); w.y = pk_bf16_rne(silu_f(v0[2]) * v1[2], silu_f(v0[3]) * v1[3]);
;                         *(u32x2e*)(Hh + (size_t)r * ldo + (cb >> 1) + 4 * fq) = w;
	v_rcp_f32_e32 v164, v164
	v_rcp_f32_e32 v165, v165
	v_rcp_f32_e32 v166, v166
	v_rcp_f32_e32 v167, v167
	v_rcp_f32_e32 v168, v168
	v_rcp_f32_e32 v169, v169
	v_rcp_f32_e32 v170, v170
	v_rcp_f32_e32 v171, v171
	v_pk_mul_f32 v[44:45], v[44:45], v[164:165]
	v_pk_mul_f32 v[46:47], v[46:47], v[166:167]
	v_pk_mul_f32 v[36:37], v[36:37], v[168:169]
	v_pk_mul_f32 v[38:39], v[38:39], v[170:171]
	v_pk_mul_f32 v[44:45], v[40:41], v[44:45]
	v_pk_mul_f32 v[46:47], v[42:43], v[46:47]
	v_pk_mul_f32 v[36:37], v[32:33], v[36:37]
	v_pk_mul_f32 v[38:39], v[34:35], v[38:39]
	v_cvt_pk_bf16_f32 v180, v44, v45
	v_cvt_pk_bf16_f32 v181, v46, v47
	v_cvt_pk_bf16_f32 v182, v36, v37
	v_cvt_pk_bf16_f32 v183, v38, v39
	global_store_dwordx2 v[160:161], v[180:181], off
	global_store_dwordx2 v[160:161], v[182:183], off offset:128
	s_nop 1
	v_lshl_add_u64 v[160:161], v[160:161], 0, s[4:5]
	v_mul_f32_e32 v164, 0xbfb8aa3b, v28
	v_mul_f32_e32 v165, 0xbfb8aa3b, v29
	v_mul_f32_e32 v166, 0xbfb8aa3b, v30
	v_mul_f32_e32 v167, 0xbfb8aa3b, v31
	v_mul_f32_e32 v168, 0xbfb8aa3b, v20
	v_mul_f32_e32 v169, 0xbfb8aa3b, v21
	v_mul_f32_e32 v170, 0xbfb8aa3b, v22
	v_mul_f32_e32 v171, 0xbfb8aa3b, v23
	v_exp_f32_e32 v164, v164
	v_exp_f32_e32 v165, v165
	v_exp_f32_e32 v166, v166
	v_exp_f32_e32 v167, v167
	v_exp_f32_e32 v168, v168
	v_exp_f32_e32 v169, v169
	v_exp_f32_e32 v170, v170
	v_exp_f32_e32 v171, v171
	v_add_f32_e32 v164, 1.0, v164
	v_add_f32_e32 v165, 1.0, v165
	v_add_f32_e32 v166, 1.0, v166
	v_add_f32_e32 v167, 1.0, v167
	v_add_f32_e32 v168, 1.0, v168
	v_add_f32_e32 v169, 1.0, v169
	v_add_f32_e32 v170, 1.0, v170
	v_add_f32_e32 v171, 1.0, v171
	v_rcp_f32_e32 v164, v164
	v_rcp_f32_e32 v165, v165
	v_rcp_f32_e32 v166, v166
	v_rcp_f32_e32 v167, v167
	v_rcp_f32_e32 v168, v168
	v_rcp_f32_e32 v169, v169
	v_rcp_f32_e32 v170, v170
	v_rcp_f32_e32 v171, v171
	v_pk_mul_f32 v[28:29], v[28:29], v[164:165]
	v_pk_mul_f32 v[30:31], v[30:31], v[166:167]
	v_pk_mul_f32 v[20:21], v[20:21], v[168:169]
	v_pk_mul_f32 v[22:23], v[22:23], v[170:171]
	v_pk_mul_f32 v[28:29], v[24:25], v[28:29]
	v_pk_mul_f32 v[30:31], v[26:27], v[30:31]
	v_pk_mul_f32 v[20:21], v[16:17], v[20:21]
	v_pk_mul_f32 v[22:23], v[18:19], v[22:23]
	v_cvt_pk_bf16_f32 v176, v28, v29
	v_cvt_pk_bf16_f32 v177, v30, v31
	v_cvt_pk_bf16_f32 v178, v20, v21
	v_cvt_pk_bf16_f32 v179, v22, v23
	global_store_dwordx2 v[160:161], v[176:177], off
	global_store_dwordx2 v[160:161], v[178:179], off offset:128
	s_nop 1
	v_lshl_add_u64 v[160:161], v[160:161], 0, s[4:5]
	v_mul_f32_e32 v164, 0xbfb8aa3b, v12
	v_mul_f32_e32 v165, 0xbfb8aa3b, v13
	v_mul_f32_e32 v166, 0xbfb8aa3b, v14
	v_mul_f32_e32 v167, 0xbfb8aa3b, v15
	v_mul_f32_e32 v168, 0xbfb8aa3b, v4
	v_mul_f32_e32 v169, 0xbfb8aa3b, v5
	v_mul_f32_e32 v170, 0xbfb8aa3b, v6
	v_mul_f32_e32 v171, 0xbfb8aa3b, v7
	v_exp_f32_e32 v164, v164
	v_exp_f32_e32 v165, v165
	v_exp_f32_e32 v166, v166
	v_exp_f32_e32 v167, v167
	v_exp_f32_e32 v168, v168
	v_exp_f32_e32 v169, v169
	v_exp_f32_e32 v170, v170
	v_exp_f32_e32 v171, v171
	v_add_f32_e32 v164, 1.0, v164
	v_add_f32_e32 v165, 1.0, v165
	v_add_f32_e32 v166, 1.0, v166
	v_add_f32_e32 v167, 1.0, v167
	v_add_f32_e32 v168, 1.0, v168
	v_add_f32_e32 v169, 1.0, v169
	v_add_f32_e32 v170, 1.0, v170
	v_add_f32_e32 v171, 1.0, v171
	v_rcp_f32_e32 v164, v164
	v_rcp_f32_e32 v165, v165
	v_rcp_f32_e32 v166, v166
	v_rcp_f32_e32 v167, v167
	v_rcp_f32_e32 v168, v168
	v_rcp_f32_e32 v169, v169
	v_rcp_f32_e32 v170, v170
	v_rcp_f32_e32 v171, v171
	v_pk_mul_f32 v[12:13], v[12:13], v[164:165]
	v_pk_mul_f32 v[14:15], v[14:15], v[166:167]
	v_pk_mul_f32 v[4:5], v[4:5], v[168:169]
	v_pk_mul_f32 v[6:7], v[6:7], v[170:171]
	v_pk_mul_f32 v[12:13], v[8:9], v[12:13]
	v_pk_mul_f32 v[14:15], v[10:11], v[14:15]
	v_pk_mul_f32 v[4:5], v[0:1], v[4:5]
	v_pk_mul_f32 v[6:7], v[2:3], v[6:7]
	v_cvt_pk_bf16_f32 v180, v12, v13
	v_cvt_pk_bf16_f32 v181, v14, v15
	v_cvt_pk_bf16_f32 v182, v4, v5
	v_cvt_pk_bf16_f32 v183, v6, v7
	global_store_dwordx2 v[160:161], v[180:181], off
	global_store_dwordx2 v[160:161], v[182:183], off offset:128
	s_branch .LBB0_562
